# P4: k=1024 row (alt item) distributed over all 32 WGs per XCD group as a pre-loop slice instead of 4 WGs x 512 rows
# speedup vs baseline: 1.0032x; 1.0032x over previous
; DI int tid_() { int t = threadIdx.x; asm volatile("" : "+v"(t)); return t; }
; DI float bf_lo(unsigned u) { return __uint_as_float(u << 16); }
; DI float bf_hi(unsigned u) { return __uint_as_float(u & 0xffff0000u); }
; DI bf16_t f2bf(float f) { return (bf16_t)(pk_bf16(f, 0.f) & 0xffffu); }
; DI void phase4(const Params& p, char* smem) {
;     ...
;     } else if (it < nDft + nAlt) {
;       const int b = xcd * 4 + (it - nDft);
;       const int tl_ = tid_();
;       const int lane_ = tl_ & 63;
;       for (int m = tl_ >> 6; m < 512; m += NWV) {
;         const bf16_t* rowp = p.ABt + (size_t)(b * 512 + m) * 4096 + lane_ * 8;
;         float sacc = 0.f;
; #pragma unroll
;         for (int i = 0; i < 4; ++i) {
;           const uint4 u = *(const uint4*)(rowp + 512 * i);
;           sacc += (bf_lo(u.x) - bf_hi(u.x)) + (bf_lo(u.y) - bf_hi(u.y)) + (bf_lo(u.z) - bf_hi(u.z)) + (bf_lo(u.w) - bf_hi(u.w));
;         }
;         sacc = wave_sum(sacc);
;         if (lane_ == 0) p.four_o[(size_t)(b * SEQ + 1024) * 512 + m] = f2bf(sacc * (1.f / 512.f));
;       }
.LBB0_535:
	s_or_b64 exec, exec, s[4:5]
	s_cmpk_gt_u32 s2, 0x61f
	v_mov_b32_e32 v0, v220
	s_barrier
	s_cbranch_scc1 .LBB0_645
	v_readlane_b32 s6, v252, 3
	s_load_dwordx4 s[24:27], s[0:1], 0x108
	s_load_dwordx8 s[16:23], s[0:1], 0xe8
	s_load_dwordx2 s[14:15], s[0:1], 0x40
	s_load_dwordx2 s[28:29], s[0:1], 0xa8
	s_lshl_b32 s45, s6, 7
	s_addk_i32 s45, 0xffbc
	s_waitcnt lgkmcnt(0)
	s_add_u32 s60, s20, 0x80
	s_addc_u32 s61, s21, 0
	s_add_i32 s63, s45, s96
	s_add_u32 s64, s18, 0x3000
	s_addc_u32 s65, s19, 0
	s_lshl_b32 s4, s6, 13
	s_lshl_b32 s5, s96, 11
	s_add_i32 s4, s4, s5
	s_add_i32 s36, s4, 0xfffe0400
	s_add_i32 s4, s96, s62
	s_lshl_b32 s4, s4, 9
	s_lshl_b32 s66, s95, 11
	s_add_i32 s67, s4, 0xffff8000
	s_lshl_b32 s68, s95, 9
	s_add_u32 s69, s24, 0x100
	s_addc_u32 s70, s25, 0
	s_lshl_b32 s71, s6, 23
	s_lshl_b32 s76, s96, 5
	s_lshl_b32 s77, s95, 5
	s_add_u32 s38, s28, 0x100
	s_addc_u32 s39, s29, 0
	s_add_u32 s78, s24, 0x1100
	v_and_b32_e32 v1, 31, v0
	s_waitcnt vmcnt(1)
	v_and_b32_e32 v2, 0xc0, v0
	s_waitcnt vmcnt(0)
	v_ashrrev_i32_e32 v3, 2, v0
	v_lshrrev_b32_e32 v0, 3, v0
	s_addc_u32 s79, s25, 0
	v_mbcnt_hi_u32_b32 v201, -1, v221
	s_movk_i32 s59, 0xffc0
	v_and_or_b32 v199, v0, 4, v2
	s_add_u32 s40, s28, 0x480100
	v_and_b32_e32 v0, 64, v201
	s_movk_i32 s58, 0xc0
	v_and_or_b32 v198, v3, s59, v1
	s_mov_b64 s[30:31], 0x80
	s_mov_b64 s[34:35], 0x3000
	s_addc_u32 s41, s29, 0
	s_mov_b32 s43, 0
	v_mov_b32_e32 v169, 0
	s_movk_i32 s80, 0x200
	s_movk_i32 s81, 0x100
	s_movk_i32 s82, 0x60
	v_mov_b32_e32 v200, 0x260
	s_mov_b32 s83, 0x8000
	s_mov_b32 s44, 0x3b000000
	s_movk_i32 s84, 0x1f7
	s_movk_i32 s85, 0x80
	s_mov_b64 s[46:47], 0x1000
	s_movk_i32 s86, 0x401
	s_movk_i32 s87, 0x3ff
	s_movk_i32 s88, 0x400
	v_xor_b32_e32 v202, 32, v201
	v_add_u32_e32 v203, 64, v0
	v_mov_b32_e32 v204, 12
	v_mov_b32_e32 v205, 0x1800
	s_mov_b32 s89, s96
	s_mov_b32 s90, s96
	s_and_b32 s100, s96, 7
	s_lshl_b32 s100, s100, 6
	s_lshr_b32 s98, s96, 3
	s_add_i32 s98, s98, s62
	s_lshl_b32 s101, s98, 9
	s_lshl_b32 s98, s98, 11
	s_addk_i32 s98, 0x400
	s_mov_b32 s99, 0
	v_mov_b32_e32 v0, v220
	s_nop 0
	v_ashrrev_i32_e32 v2, 6, v0
	v_cmp_gt_i32_e32 vcc, s80, v2
	s_and_saveexec_b64 s[6:7], vcc
	s_cbranch_execz .Lalt_exit
	v_cmp_lt_i32_e32 vcc, v202, v203
	v_and_b32_e32 v11, 63, v0
	s_mov_b32 s37, s43
	v_cndmask_b32_e32 v0, v201, v202, vcc
	v_lshlrev_b32_e32 v4, 2, v0
	v_xor_b32_e32 v0, 16, v201
	v_cmp_lt_i32_e32 vcc, v0, v203
	s_lshl_b64 s[4:5], s[98:99], 10
	s_add_u32 s4, s26, s4
	v_cndmask_b32_e32 v0, v201, v0, vcc
	v_lshlrev_b32_e32 v5, 2, v0
	v_xor_b32_e32 v0, 8, v201
	v_cmp_lt_i32_e32 vcc, v0, v203
	v_ashrrev_i32_e32 v3, 31, v2
	s_addc_u32 s5, s27, s5
	v_cndmask_b32_e32 v0, v201, v0, vcc
	v_lshlrev_b32_e32 v6, 2, v0
	v_xor_b32_e32 v0, 4, v201
	v_cmp_lt_i32_e32 vcc, v0, v203
	v_add_u32_e32 v10, -8, v2
	v_add_u32_e32 v2, s100, v2
	s_mov_b64 s[8:9], 0
	v_cndmask_b32_e32 v0, v201, v0, vcc
	v_lshlrev_b32_e32 v7, 2, v0
	v_xor_b32_e32 v0, 2, v201
	v_cmp_lt_i32_e32 vcc, v0, v203
	s_nop 1
	v_cndmask_b32_e32 v0, v201, v0, vcc
	v_lshlrev_b32_e32 v8, 2, v0
	v_xor_b32_e32 v0, 1, v201
	v_cmp_lt_i32_e32 vcc, v0, v203
	s_nop 1
	v_cndmask_b32_e32 v0, v201, v0, vcc
	v_lshlrev_b32_e32 v9, 2, v0
	v_lshl_add_u64 v[0:1], v[2:3], 1, s[4:5]
	v_add_u32_e32 v2, s101, v2
	v_ashrrev_i32_e32 v3, 31, v2
	v_lshlrev_b64 v[2:3], 13, v[2:3]
	v_lshl_or_b32 v2, v11, 4, v2
	v_cmp_eq_u32_e32 vcc, 0, v11
	v_lshl_add_u64 v[2:3], s[24:25], 0, v[2:3]
	s_branch .Lalt_loop
.Lalt_latch:
	s_or_b64 exec, exec, s[4:5]
	v_add_u32_e32 v10, 8, v10
	v_cmp_lt_i32_e64 s[4:5], 55, v10
	s_or_b64 s[8:9], s[4:5], s[8:9]
	s_mov_b64 s[4:5], 0x10000
	v_lshl_add_u64 v[0:1], v[0:1], 0, 16
	v_lshl_add_u64 v[2:3], v[2:3], 0, s[4:5]
	s_andn2_b64 exec, exec, s[8:9]
	s_cbranch_execz .Lalt_exit

; DI float bf_lo(unsigned u) { return __uint_as_float(u << 16); }
; DI float bf_hi(unsigned u) { return __uint_as_float(u & 0xffff0000u); }
; DI bf16_t f2bf(float f) { return (bf16_t)(pk_bf16(f, 0.f) & 0xffffu); }
; DI void phase4(const Params& p, char* smem) {
;     ...
;       for (int m = tl_ >> 6; m < 512; m += NWV) {
;         const bf16_t* rowp = p.ABt + (size_t)(b * 512 + m) * 4096 + lane_ * 8;
;         float sacc = 0.f;
; #pragma unroll
;         for (int i = 0; i < 4; ++i) {
;           const uint4 u = *(const uint4*)(rowp + 512 * i);
;           sacc += (bf_lo(u.x) - bf_hi(u.x)) + (bf_lo(u.y) - bf_hi(u.y)) + (bf_lo(u.z) - bf_hi(u.z)) + (bf_lo(u.w) - bf_hi(u.w));
;         }
;         sacc = wave_sum(sacc);
;         if (lane_ == 0) p.four_o[(size_t)(b * SEQ + 1024) * 512 + m] = f2bf(sacc * (1.f / 512.f));
;       }
.Lalt_exit:
	s_or_b64 exec, exec, s[6:7]
	s_branch .LBB0_539

; DI unsigned pk_bf16(float lo, float hi) { f32x2v v = {lo, hi}; bf16x2v b = __builtin_convertvector(v, bf16x2v); return __builtin_bit_cast(unsigned, b); }
; DI void phase4(const Params& p, char* smem) {
;     ...
;           if (kpos <= 1024) {
;             bf16_t* d = p.four_o + (size_t)(b * SEQ + kpos) * 512 + moff;
; #pragma unroll
;             for (int q = 0; q < 4; ++q) {
;               uint2 ou; ou.x = pk_bf16((acc1[tm][tn][4 * q] - acc2[tm][tn][4 * q]) * sc, (acc1[tm][tn][4 * q + 1] - acc2[tm][tn][4 * q + 1]) * sc);
;               ou.y = pk_bf16((acc1[tm][tn][4 * q + 2] - acc2[tm][tn][4 * q + 2]) * sc, (acc1[tm][tn][4 * q + 3] - acc2[tm][tn][4 * q + 3]) * sc);
;               *(uint2*)(d + 8 * q) = ou;
;             }
;           }
;           if (kpos >= 1 && kpos <= 1023) {
;             bf16_t* d = p.four_o + (size_t)(b * SEQ + 2048 - kpos) * 512 + moff;
; #pragma unroll
;             for (int q = 0; q < 4; ++q) {
;               uint2 ou; ou.x = pk_bf16((acc1[tm][tn][4 * q] + acc2[tm][tn][4 * q]) * sc, (acc1[tm][tn][4 * q + 1] + acc2[tm][tn][4 * q + 1]) * sc);
;               ou.y = pk_bf16((acc1[tm][tn][4 * q + 2] + acc2[tm][tn][4 * q + 2]) * sc, (acc1[tm][tn][4 * q + 3] + acc2[tm][tn][4 * q + 3]) * sc);
;               *(uint2*)(d + 8 * q) = ou;
;             }
;           }
.LBB0_638:
	s_or_b64 exec, exec, s[4:5]
	s_and_saveexec_b64 s[4:5], s[8:9]
	s_cbranch_execz .LBB0_537
	s_branch .LBB0_644
.LBB0_640:
	v_mov_b32_e32 v51, v169
	v_pk_add_f32 v[34:35], v[34:35], v[98:99]
	v_pk_add_f32 v[32:33], v[32:33], v[96:97]
	v_lshl_add_u64 v[52:53], s[26:27], 0, v[50:51]
	v_pk_mul_f32 v[32:33], v[32:33], s[44:45] op_sel_hi:[1,0]
	v_pk_mul_f32 v[34:35], v[34:35], s[44:45] op_sel_hi:[1,0]
	v_lshl_add_u64 v[52:53], v[52:53], 0, v[168:169]
	v_pk_add_f32 v[38:39], v[38:39], v[102:103]
	v_pk_add_f32 v[36:37], v[36:37], v[100:101]
	v_cvt_pk_bf16_f32 v32, v32, v33
	v_cvt_pk_bf16_f32 v33, v34, v35
	global_store_dwordx2 v[52:53], v[32:33], off
	v_pk_mul_f32 v[32:33], v[36:37], s[44:45] op_sel_hi:[1,0]
	v_pk_mul_f32 v[34:35], v[38:39], s[44:45] op_sel_hi:[1,0]
	v_pk_add_f32 v[42:43], v[42:43], v[106:107]
	v_pk_add_f32 v[40:41], v[40:41], v[104:105]
	v_cvt_pk_bf16_f32 v32, v32, v33
	v_cvt_pk_bf16_f32 v33, v34, v35
	global_store_dwordx2 v[52:53], v[32:33], off offset:16
	v_pk_mul_f32 v[32:33], v[40:41], s[44:45] op_sel_hi:[1,0]
	v_pk_mul_f32 v[34:35], v[42:43], s[44:45] op_sel_hi:[1,0]
	v_pk_add_f32 v[46:47], v[46:47], v[110:111]
	v_pk_add_f32 v[44:45], v[44:45], v[108:109]
	v_cvt_pk_bf16_f32 v32, v32, v33
	v_cvt_pk_bf16_f32 v33, v34, v35
	global_store_dwordx2 v[52:53], v[32:33], off offset:32
	v_pk_mul_f32 v[32:33], v[44:45], s[44:45] op_sel_hi:[1,0]
	v_pk_mul_f32 v[34:35], v[46:47], s[44:45] op_sel_hi:[1,0]
	v_cvt_pk_bf16_f32 v32, v32, v33
	v_cvt_pk_bf16_f32 v33, v34, v35
	global_store_dwordx2 v[52:53], v[32:33], off offset:48
	s_or_b64 exec, exec, s[10:11]
	s_and_saveexec_b64 s[10:11], vcc
	s_cbranch_execz .LBB0_636

; __global__ void __launch_bounds__(NTH, 2) mega_kernel(Params p) {
;   cg::grid_group grid = cg::this_grid();
;   __shared__ __attribute__((aligned(16))) char smem[SMEM_BYTES];
	.amdhsa_kernel _Z11mega_kernel6Params
		.amdhsa_group_segment_fixed_size 147456
		.amdhsa_private_segment_fixed_size 0
		.amdhsa_kernarg_size 1424
		.amdhsa_user_sgpr_count 2
		.amdhsa_user_sgpr_dispatch_ptr 0
		.amdhsa_user_sgpr_queue_ptr 0
		.amdhsa_user_sgpr_kernarg_segment_ptr 1
		.amdhsa_user_sgpr_dispatch_id 0
		.amdhsa_user_sgpr_kernarg_preload_length 0
		.amdhsa_user_sgpr_kernarg_preload_offset 0
		.amdhsa_user_sgpr_private_segment_size 0
		.amdhsa_uses_dynamic_stack 0
		.amdhsa_enable_private_segment 0
		.amdhsa_system_sgpr_workgroup_id_x 1
		.amdhsa_system_sgpr_workgroup_id_y 0
		.amdhsa_system_sgpr_workgroup_id_z 0
		.amdhsa_system_sgpr_workgroup_info 0
		.amdhsa_system_vgpr_workitem_id 2
		.amdhsa_next_free_vgpr 253
		.amdhsa_next_free_sgpr 102
		.amdhsa_accum_offset 256
		.amdhsa_reserve_vcc 1
		.amdhsa_float_round_mode_32 0
		.amdhsa_float_round_mode_16_64 0
		.amdhsa_float_denorm_mode_32 3
		.amdhsa_float_denorm_mode_16_64 3
		.amdhsa_dx10_clamp 1
		.amdhsa_ieee_mode 1
		.amdhsa_fp16_overflow 0
		.amdhsa_tg_split 0
		.amdhsa_exception_fp_ieee_invalid_op 0
		.amdhsa_exception_fp_denorm_src 0
		.amdhsa_exception_fp_ieee_div_zero 0
		.amdhsa_exception_fp_ieee_overflow 0
		.amdhsa_exception_fp_ieee_underflow 0
		.amdhsa_exception_fp_ieee_inexact 0
		.amdhsa_exception_int_div_zero 0
	.end_amdhsa_kernel

; __global__ void __launch_bounds__(NTH, 2) mega_kernel(Params p) {
;   cg::grid_group grid = cg::this_grid();
;   __shared__ __attribute__((aligned(16))) char smem[SMEM_BYTES];
amdhsa.kernels:
  - .agpr_count:     0
    .args:
      - .offset:         0
        .size:           1168
        .value_kind:     by_value
      - .offset:         1168
        .size:           4
        .value_kind:     hidden_block_count_x
      - .offset:         1172
        .size:           4
        .value_kind:     hidden_block_count_y
      - .offset:         1176
        .size:           4
        .value_kind:     hidden_block_count_z
      - .offset:         1180
        .size:           2
        .value_kind:     hidden_group_size_x
      - .offset:         1182
        .size:           2
        .value_kind:     hidden_group_size_y
      - .offset:         1184
        .size:           2
        .value_kind:     hidden_group_size_z
      - .offset:         1186
        .size:           2
        .value_kind:     hidden_remainder_x
      - .offset:         1188
        .size:           2
        .value_kind:     hidden_remainder_y
      - .offset:         1190
        .size:           2
        .value_kind:     hidden_remainder_z
      - .offset:         1208
        .size:           8
        .value_kind:     hidden_global_offset_x
      - .offset:         1216
        .size:           8
        .value_kind:     hidden_global_offset_y
      - .offset:         1224
        .size:           8
        .value_kind:     hidden_global_offset_z
      - .offset:         1232
        .size:           2
        .value_kind:     hidden_grid_dims
      - .offset:         1256
        .size:           8
        .value_kind:     hidden_multigrid_sync_arg
    .group_segment_fixed_size: 147456
    .kernarg_segment_align: 8
    .kernarg_segment_size: 1424
    .language:       OpenCL C
    .language_version:
      - 2
      - 0
    .max_flat_workgroup_size: 512
    .name:           _Z11mega_kernel6Params
    .private_segment_fixed_size: 0
    .sgpr_count:     108
    .sgpr_spill_count: 4
    .symbol:         _Z11mega_kernel6Params.kd
    .uniform_work_group_size: 1
    .uses_dynamic_stack: false
    .vgpr_count:     253
    .vgpr_spill_count: 0
    .wavefront_size: 64
